# v26 + next-loop first-tile and Q loads hoisted to the top of the diff-attention copy-1 and copy-3 epilogues
# speedup vs baseline: 1.0092x; 1.0030x over previous
.Lfo_out_c1:
	global_load_dwordx4 v[122:125], v[150:151], off offset:2176
	global_load_dwordx4 v[134:137], v[152:153], off
	global_load_dwordx4 v[138:141], v[154:155], off
	global_load_dwordx4 v[114:117], v[156:157], off offset:128
	global_load_dwordx4 v[118:121], v[156:157], off offset:160
	global_load_dwordx4 v[126:129], v[156:157], off offset:192
	global_load_dwordx4 v[130:133], v[156:157], off offset:224
	v_mov_b32_e32 v241, v239
	s_nop 1
	v_permlane32_swap_b32_e32 v239, v241
	v_add_f32_e32 v239, v239, v241
	v_add_u32_e32 v241, 0x12800, v174
	ds_write_b32 v241, v239 offset:59392
	v_add_u32_e32 v240, s91, v172
	v_add_u32_e32 v240, 0x12800, v240
	s_waitcnt lgkmcnt(0)
	ds_read_b128 v[66:69], v240 offset:59392
	ds_read_b128 v[70:73], v240 offset:59424
	ds_read_b128 v[74:77], v240 offset:59456
	ds_read_b128 v[78:81], v240 offset:59488
	s_waitcnt lgkmcnt(0)
	s_branch .LBB0_49
.LBB0_49:
	v_mov_b32_e32 v82, v2
	v_rcp_f32_e32 v2, v67
	v_mov_b32_e32 v83, v50
	v_mov_b32_e32 v85, v18
	v_mov_b32_e32 v50, v3
	v_mov_b32_e32 v18, v35
	v_pk_mul_f32 v[50:51], v[50:51], v[2:3] op_sel_hi:[1,0]
	v_pk_mul_f32 v[2:3], v[18:19], v[2:3] op_sel_hi:[1,0]
	v_mov_b32_e32 v18, v4
	v_rcp_f32_e32 v4, v69
	v_mov_b32_e32 v84, v34
	v_rcp_f32_e32 v34, v68
	v_mov_b32_e32 v19, v52
	v_mov_b32_e32 v69, v20
	v_mov_b32_e32 v52, v5
	v_mov_b32_e32 v20, v37
	v_pk_mul_f32 v[52:53], v[52:53], v[4:5] op_sel_hi:[1,0]
	v_pk_mul_f32 v[4:5], v[20:21], v[4:5] op_sel_hi:[1,0]
	v_mov_b32_e32 v20, v6
	v_rcp_f32_e32 v6, v71
	v_mov_b32_e32 v68, v36
	v_pk_mul_f32 v[18:19], v[18:19], v[34:35] op_sel_hi:[1,0]
	v_pk_mul_f32 v[34:35], v[68:69], v[34:35] op_sel_hi:[1,0]
	v_rcp_f32_e32 v36, v70
	v_mov_b32_e32 v21, v54
	v_mov_b32_e32 v69, v22
	v_mov_b32_e32 v54, v7
	v_mov_b32_e32 v22, v39
	v_pk_mul_f32 v[54:55], v[54:55], v[6:7] op_sel_hi:[1,0]
	v_pk_mul_f32 v[6:7], v[22:23], v[6:7] op_sel_hi:[1,0]
	v_mov_b32_e32 v22, v8
	v_rcp_f32_e32 v8, v73
	v_mov_b32_e32 v68, v38
	v_pk_mul_f32 v[20:21], v[20:21], v[36:37] op_sel_hi:[1,0]
	v_pk_mul_f32 v[36:37], v[68:69], v[36:37] op_sel_hi:[1,0]
	v_rcp_f32_e32 v38, v72
	v_mov_b32_e32 v23, v56
	v_mov_b32_e32 v69, v24
	v_mov_b32_e32 v56, v9
	v_mov_b32_e32 v24, v41
	v_pk_mul_f32 v[56:57], v[56:57], v[8:9] op_sel_hi:[1,0]
	v_pk_mul_f32 v[8:9], v[24:25], v[8:9] op_sel_hi:[1,0]
	v_mov_b32_e32 v24, v10
	v_rcp_f32_e32 v10, v75
	v_mov_b32_e32 v68, v40
	v_pk_mul_f32 v[22:23], v[22:23], v[38:39] op_sel_hi:[1,0]
	v_pk_mul_f32 v[38:39], v[68:69], v[38:39] op_sel_hi:[1,0]
	v_rcp_f32_e32 v40, v74
	v_mov_b32_e32 v25, v58
	v_mov_b32_e32 v69, v26
	v_mov_b32_e32 v58, v11
	v_mov_b32_e32 v26, v43
	v_pk_mul_f32 v[58:59], v[58:59], v[10:11] op_sel_hi:[1,0]
	v_pk_mul_f32 v[10:11], v[26:27], v[10:11] op_sel_hi:[1,0]
	v_mov_b32_e32 v26, v12
	v_rcp_f32_e32 v12, v77
	v_mov_b32_e32 v68, v42
	v_pk_mul_f32 v[24:25], v[24:25], v[40:41] op_sel_hi:[1,0]
	v_pk_mul_f32 v[40:41], v[68:69], v[40:41] op_sel_hi:[1,0]
	v_rcp_f32_e32 v42, v76
	v_mov_b32_e32 v27, v60
	v_mov_b32_e32 v69, v28
	v_mov_b32_e32 v60, v13
	v_mov_b32_e32 v28, v45
	v_pk_mul_f32 v[60:61], v[60:61], v[12:13] op_sel_hi:[1,0]
	v_pk_mul_f32 v[12:13], v[28:29], v[12:13] op_sel_hi:[1,0]
	v_mov_b32_e32 v28, v14
	v_rcp_f32_e32 v14, v79
	v_mov_b32_e32 v68, v44
	v_rcp_f32_e32 v66, v66
	v_pk_mul_f32 v[26:27], v[26:27], v[42:43] op_sel_hi:[1,0]
	v_pk_mul_f32 v[42:43], v[68:69], v[42:43] op_sel_hi:[1,0]
	v_rcp_f32_e32 v44, v78
	v_mov_b32_e32 v29, v62
	v_mov_b32_e32 v69, v30
	v_mov_b32_e32 v62, v15
	v_mov_b32_e32 v30, v47
	v_pk_mul_f32 v[62:63], v[62:63], v[14:15] op_sel_hi:[1,0]
	v_pk_mul_f32 v[14:15], v[30:31], v[14:15] op_sel_hi:[1,0]
	v_mov_b32_e32 v30, v16
	v_rcp_f32_e32 v16, v81
	v_readlane_b32 s10, v251, 9
	v_mov_b32_e32 v68, v46
	v_pk_mul_f32 v[82:83], v[82:83], v[66:67] op_sel_hi:[1,0]
	v_add_u32_e32 v160, s10, v237
	v_pk_mul_f32 v[66:67], v[84:85], v[66:67] op_sel_hi:[1,0]
	v_pk_mul_f32 v[28:29], v[28:29], v[44:45] op_sel_hi:[1,0]
	v_pk_mul_f32 v[44:45], v[68:69], v[44:45] op_sel_hi:[1,0]
	v_mov_b32_e32 v31, v64
	v_mov_b32_e32 v69, v32
	v_mov_b32_e32 v64, v17
	v_mov_b32_e32 v32, v49
	v_mov_b32_e32 v68, v48
	v_pk_mul_f32 v[64:65], v[64:65], v[16:17] op_sel_hi:[1,0]
	v_pk_mul_f32 v[16:17], v[32:33], v[16:17] op_sel_hi:[1,0]
	v_cvt_pk_bf16_f32 v33, v82, v83
	v_add_u32_e32 v32, 0, v160
	v_cvt_pk_bf16_f32 v48, v66, v67
	ds_write2st64_b32 v32, v33, v48 offset1:1
	v_cvt_pk_bf16_f32 v33, v50, v51
	v_cvt_pk_bf16_f32 v2, v2, v3
	ds_write2st64_b32 v32, v33, v2 offset0:2 offset1:3
	v_cvt_pk_bf16_f32 v2, v18, v19
	v_cvt_pk_bf16_f32 v3, v34, v35
	ds_write2st64_b32 v32, v2, v3 offset0:4 offset1:5
	v_cvt_pk_bf16_f32 v2, v52, v53
	v_cvt_pk_bf16_f32 v3, v4, v5
	ds_write2st64_b32 v32, v2, v3 offset0:6 offset1:7
	v_cvt_pk_bf16_f32 v2, v20, v21
	v_cvt_pk_bf16_f32 v3, v36, v37
	ds_write2st64_b32 v32, v2, v3 offset0:8 offset1:9
	v_cvt_pk_bf16_f32 v2, v54, v55
	v_cvt_pk_bf16_f32 v3, v6, v7
	ds_write2st64_b32 v32, v2, v3 offset0:10 offset1:11
	v_cvt_pk_bf16_f32 v2, v22, v23
	v_cvt_pk_bf16_f32 v3, v38, v39
	ds_write2st64_b32 v32, v2, v3 offset0:12 offset1:13
	v_cvt_pk_bf16_f32 v2, v56, v57
	v_cvt_pk_bf16_f32 v3, v8, v9
	ds_write2st64_b32 v32, v2, v3 offset0:14 offset1:15
	v_cvt_pk_bf16_f32 v2, v24, v25
	v_cvt_pk_bf16_f32 v3, v40, v41
	v_rcp_f32_e32 v46, v80
	ds_write2st64_b32 v32, v2, v3 offset0:16 offset1:17
	v_cvt_pk_bf16_f32 v2, v58, v59
	v_cvt_pk_bf16_f32 v3, v10, v11
	ds_write2st64_b32 v32, v2, v3 offset0:18 offset1:19
	v_cvt_pk_bf16_f32 v2, v26, v27
	v_cvt_pk_bf16_f32 v3, v42, v43
	ds_write2st64_b32 v32, v2, v3 offset0:20 offset1:21
	v_cvt_pk_bf16_f32 v2, v60, v61
	v_cvt_pk_bf16_f32 v3, v12, v13
	ds_write2st64_b32 v32, v2, v3 offset0:22 offset1:23
	v_cvt_pk_bf16_f32 v2, v28, v29
	v_cvt_pk_bf16_f32 v3, v44, v45
	v_pk_mul_f32 v[30:31], v[30:31], v[46:47] op_sel_hi:[1,0]
	v_pk_mul_f32 v[46:47], v[68:69], v[46:47] op_sel_hi:[1,0]
	ds_write2st64_b32 v32, v2, v3 offset0:24 offset1:25
	v_cvt_pk_bf16_f32 v2, v62, v63
	v_cvt_pk_bf16_f32 v3, v14, v15
	ds_write2st64_b32 v32, v2, v3 offset0:26 offset1:27
	v_cvt_pk_bf16_f32 v2, v30, v31
	v_cvt_pk_bf16_f32 v3, v46, v47
	ds_write2st64_b32 v32, v2, v3 offset0:28 offset1:29
	v_cvt_pk_bf16_f32 v2, v64, v65
	v_cvt_pk_bf16_f32 v3, v16, v17
	ds_write2st64_b32 v32, v2, v3 offset0:30 offset1:31
	v_mov_b32_e32 v16, v1
	v_mov_b32_e32 v17, v1
	v_mov_b32_e32 v2, v1
	v_mov_b32_e32 v3, v1
	v_mov_b32_e32 v4, v1
	v_mov_b32_e32 v5, v1
	v_mov_b32_e32 v6, v1
	v_mov_b32_e32 v7, v1
	v_mov_b32_e32 v8, v1
	v_mov_b32_e32 v9, v1
	v_mov_b32_e32 v10, v1
	v_mov_b32_e32 v11, v1
	v_mov_b32_e32 v12, v1
	v_mov_b32_e32 v13, v1
	v_mov_b32_e32 v14, v1
	v_mov_b32_e32 v15, v1
	v_mov_b64_e32 v[64:65], v[16:17]
	v_mov_b64_e32 v[32:33], v[16:17]
	v_mov_b64_e32 v[48:49], v[16:17]
	v_mov_b64_e32 v[80:81], v[16:17]
	v_lshl_add_u64 v[150:151], s[46:47], 0, v[158:159]
	s_mov_b32 s10, 63
	s_mov_b64 s[60:61], 0
	s_mov_b32 s22, 1
	v_mov_b64_e32 v[62:63], v[14:15]
	v_mov_b64_e32 v[60:61], v[12:13]
	v_mov_b64_e32 v[58:59], v[10:11]
	v_mov_b64_e32 v[56:57], v[8:9]
	v_mov_b64_e32 v[54:55], v[6:7]
	v_mov_b64_e32 v[52:53], v[4:5]
	v_mov_b64_e32 v[50:51], v[2:3]
	v_mov_b64_e32 v[30:31], v[14:15]
	v_mov_b64_e32 v[28:29], v[12:13]
	v_mov_b64_e32 v[26:27], v[10:11]
	v_mov_b64_e32 v[24:25], v[8:9]
	v_mov_b64_e32 v[22:23], v[6:7]
	v_mov_b64_e32 v[20:21], v[4:5]
	v_mov_b64_e32 v[18:19], v[2:3]
	v_mov_b64_e32 v[46:47], v[14:15]
	v_mov_b64_e32 v[44:45], v[12:13]
	v_mov_b64_e32 v[42:43], v[10:11]
	v_mov_b64_e32 v[40:41], v[8:9]
	v_mov_b64_e32 v[38:39], v[6:7]
	v_mov_b64_e32 v[36:37], v[4:5]
	v_mov_b64_e32 v[34:35], v[2:3]
	v_mov_b64_e32 v[78:79], v[14:15]
	v_mov_b64_e32 v[76:77], v[12:13]
	v_mov_b64_e32 v[74:75], v[10:11]
	v_mov_b64_e32 v[72:73], v[8:9]
	v_mov_b64_e32 v[70:71], v[6:7]
	v_mov_b64_e32 v[68:69], v[4:5]
	v_mov_b64_e32 v[66:67], v[2:3]
	s_waitcnt vmcnt(6)
	ds_write_b128 v234, v[122:125]
	s_waitcnt vmcnt(5)
	ds_write_b128 v235, v[134:137] offset:9216
	s_waitcnt vmcnt(4)
	ds_write_b128 v236, v[138:141] offset:9216
	s_waitcnt vmcnt(0) lgkmcnt(0)
	s_barrier
	v_mov_b32_e32 v238, 0
	s_mov_b32 s79, 1
	s_cmp_lt_u32 s22, s4
	s_cselect_b64 s[62:63], -1, 0
	s_cmp_ge_u32 s22, s4
	s_cbranch_scc1 .LBB0_51

.Lfo_out_c3:
	global_load_dwordx4 v[114:117], v[150:151], off offset:2176
	global_load_dwordx4 v[130:133], v[152:153], off
	global_load_dwordx4 v[138:141], v[154:155], off
	global_load_dwordx4 v[118:121], v[156:157], off offset:128
	global_load_dwordx4 v[122:125], v[156:157], off offset:160
	global_load_dwordx4 v[126:129], v[156:157], off offset:192
	global_load_dwordx4 v[134:137], v[156:157], off offset:224
	v_mov_b32_e32 v191, v243
	s_nop 1
	v_permlane32_swap_b32_e32 v243, v191
	v_add_f32_e32 v243, v243, v191
	v_add_u32_e32 v191, 0x12800, v180
	ds_write_b32 v191, v243 offset:59392
	v_add_u32_e32 v190, s91, v178
	v_add_u32_e32 v190, 0x12800, v190
	s_waitcnt lgkmcnt(0)
	ds_read_b128 v[66:69], v190 offset:59392
	ds_read_b128 v[70:73], v190 offset:59424
	ds_read_b128 v[74:77], v190 offset:59456
	ds_read_b128 v[78:81], v190 offset:59488
	s_waitcnt lgkmcnt(0)
	s_branch .LBB0_79
.LBB0_79:
	v_mov_b32_e32 v82, v2
	v_rcp_f32_e32 v2, v67
	v_mov_b32_e32 v83, v50
	v_mov_b32_e32 v85, v18
	v_mov_b32_e32 v50, v3
	v_mov_b32_e32 v18, v35
	v_pk_mul_f32 v[50:51], v[50:51], v[2:3] op_sel_hi:[1,0]
	v_pk_mul_f32 v[2:3], v[18:19], v[2:3] op_sel_hi:[1,0]
	v_mov_b32_e32 v18, v4
	v_rcp_f32_e32 v4, v69
	v_mov_b32_e32 v84, v34
	v_rcp_f32_e32 v34, v68
	v_mov_b32_e32 v19, v52
	v_mov_b32_e32 v69, v20
	v_mov_b32_e32 v52, v5
	v_mov_b32_e32 v20, v37
	v_pk_mul_f32 v[52:53], v[52:53], v[4:5] op_sel_hi:[1,0]
	v_pk_mul_f32 v[4:5], v[20:21], v[4:5] op_sel_hi:[1,0]
	v_mov_b32_e32 v20, v6
	v_rcp_f32_e32 v6, v71
	v_mov_b32_e32 v68, v36
	v_pk_mul_f32 v[18:19], v[18:19], v[34:35] op_sel_hi:[1,0]
	v_pk_mul_f32 v[34:35], v[68:69], v[34:35] op_sel_hi:[1,0]
	v_rcp_f32_e32 v36, v70
	v_mov_b32_e32 v21, v54
	v_mov_b32_e32 v69, v22
	v_mov_b32_e32 v54, v7
	v_mov_b32_e32 v22, v39
	v_pk_mul_f32 v[54:55], v[54:55], v[6:7] op_sel_hi:[1,0]
	v_pk_mul_f32 v[6:7], v[22:23], v[6:7] op_sel_hi:[1,0]
	v_mov_b32_e32 v22, v8
	v_rcp_f32_e32 v8, v73
	v_mov_b32_e32 v68, v38
	v_pk_mul_f32 v[20:21], v[20:21], v[36:37] op_sel_hi:[1,0]
	v_pk_mul_f32 v[36:37], v[68:69], v[36:37] op_sel_hi:[1,0]
	v_rcp_f32_e32 v38, v72
	v_mov_b32_e32 v23, v56
	v_mov_b32_e32 v69, v24
	v_mov_b32_e32 v56, v9
	v_mov_b32_e32 v24, v41
	v_pk_mul_f32 v[56:57], v[56:57], v[8:9] op_sel_hi:[1,0]
	v_pk_mul_f32 v[8:9], v[24:25], v[8:9] op_sel_hi:[1,0]
	v_mov_b32_e32 v24, v10
	v_rcp_f32_e32 v10, v75
	v_mov_b32_e32 v68, v40
	v_pk_mul_f32 v[22:23], v[22:23], v[38:39] op_sel_hi:[1,0]
	v_pk_mul_f32 v[38:39], v[68:69], v[38:39] op_sel_hi:[1,0]
	v_rcp_f32_e32 v40, v74
	v_mov_b32_e32 v25, v58
	v_mov_b32_e32 v69, v26
	v_mov_b32_e32 v58, v11
	v_mov_b32_e32 v26, v43
	v_pk_mul_f32 v[58:59], v[58:59], v[10:11] op_sel_hi:[1,0]
	v_pk_mul_f32 v[10:11], v[26:27], v[10:11] op_sel_hi:[1,0]
	v_mov_b32_e32 v26, v12
	v_rcp_f32_e32 v12, v77
	v_mov_b32_e32 v68, v42
	v_pk_mul_f32 v[24:25], v[24:25], v[40:41] op_sel_hi:[1,0]
	v_pk_mul_f32 v[40:41], v[68:69], v[40:41] op_sel_hi:[1,0]
	v_rcp_f32_e32 v42, v76
	v_mov_b32_e32 v27, v60
	v_mov_b32_e32 v69, v28
	v_mov_b32_e32 v60, v13
	v_mov_b32_e32 v28, v45
	v_pk_mul_f32 v[60:61], v[60:61], v[12:13] op_sel_hi:[1,0]
	v_pk_mul_f32 v[12:13], v[28:29], v[12:13] op_sel_hi:[1,0]
	v_mov_b32_e32 v28, v14
	v_rcp_f32_e32 v14, v79
	v_mov_b32_e32 v68, v44
	v_rcp_f32_e32 v66, v66
	v_pk_mul_f32 v[26:27], v[26:27], v[42:43] op_sel_hi:[1,0]
	v_pk_mul_f32 v[42:43], v[68:69], v[42:43] op_sel_hi:[1,0]
	v_rcp_f32_e32 v44, v78
	v_mov_b32_e32 v29, v62
	v_mov_b32_e32 v69, v30
	v_mov_b32_e32 v62, v15
	v_mov_b32_e32 v30, v47
	v_pk_mul_f32 v[62:63], v[62:63], v[14:15] op_sel_hi:[1,0]
	v_pk_mul_f32 v[14:15], v[30:31], v[14:15] op_sel_hi:[1,0]
	v_mov_b32_e32 v30, v16
	v_rcp_f32_e32 v16, v81
	v_readlane_b32 s4, v251, 9
	v_mov_b32_e32 v68, v46
	v_pk_mul_f32 v[82:83], v[82:83], v[66:67] op_sel_hi:[1,0]
	v_add_u32_e32 v160, s4, v241
	v_pk_mul_f32 v[66:67], v[84:85], v[66:67] op_sel_hi:[1,0]
	v_pk_mul_f32 v[28:29], v[28:29], v[44:45] op_sel_hi:[1,0]
	v_pk_mul_f32 v[44:45], v[68:69], v[44:45] op_sel_hi:[1,0]
	v_mov_b32_e32 v31, v64
	v_mov_b32_e32 v69, v32
	v_mov_b32_e32 v64, v17
	v_mov_b32_e32 v32, v49
	v_mov_b32_e32 v68, v48
	v_pk_mul_f32 v[64:65], v[64:65], v[16:17] op_sel_hi:[1,0]
	v_pk_mul_f32 v[16:17], v[32:33], v[16:17] op_sel_hi:[1,0]
	v_cvt_pk_bf16_f32 v33, v82, v83
	v_add_u32_e32 v32, 0, v160
	v_cvt_pk_bf16_f32 v48, v66, v67
	ds_write2st64_b32 v32, v33, v48 offset1:1
	v_cvt_pk_bf16_f32 v33, v50, v51
	v_cvt_pk_bf16_f32 v2, v2, v3
	ds_write2st64_b32 v32, v33, v2 offset0:2 offset1:3
	v_cvt_pk_bf16_f32 v2, v18, v19
	v_cvt_pk_bf16_f32 v3, v34, v35
	ds_write2st64_b32 v32, v2, v3 offset0:4 offset1:5
	v_cvt_pk_bf16_f32 v2, v52, v53
	v_cvt_pk_bf16_f32 v3, v4, v5
	ds_write2st64_b32 v32, v2, v3 offset0:6 offset1:7
	v_cvt_pk_bf16_f32 v2, v20, v21
	v_cvt_pk_bf16_f32 v3, v36, v37
	ds_write2st64_b32 v32, v2, v3 offset0:8 offset1:9
	v_cvt_pk_bf16_f32 v2, v54, v55
	v_cvt_pk_bf16_f32 v3, v6, v7
	ds_write2st64_b32 v32, v2, v3 offset0:10 offset1:11
	v_cvt_pk_bf16_f32 v2, v22, v23
	v_cvt_pk_bf16_f32 v3, v38, v39
	ds_write2st64_b32 v32, v2, v3 offset0:12 offset1:13
	v_cvt_pk_bf16_f32 v2, v56, v57
	v_cvt_pk_bf16_f32 v3, v8, v9
	ds_write2st64_b32 v32, v2, v3 offset0:14 offset1:15
	v_cvt_pk_bf16_f32 v2, v24, v25
	v_cvt_pk_bf16_f32 v3, v40, v41
	v_rcp_f32_e32 v46, v80
	ds_write2st64_b32 v32, v2, v3 offset0:16 offset1:17
	v_cvt_pk_bf16_f32 v2, v58, v59
	v_cvt_pk_bf16_f32 v3, v10, v11
	ds_write2st64_b32 v32, v2, v3 offset0:18 offset1:19
	v_cvt_pk_bf16_f32 v2, v26, v27
	v_cvt_pk_bf16_f32 v3, v42, v43
	ds_write2st64_b32 v32, v2, v3 offset0:20 offset1:21
	v_cvt_pk_bf16_f32 v2, v60, v61
	v_cvt_pk_bf16_f32 v3, v12, v13
	ds_write2st64_b32 v32, v2, v3 offset0:22 offset1:23
	v_cvt_pk_bf16_f32 v2, v28, v29
	v_cvt_pk_bf16_f32 v3, v44, v45
	v_pk_mul_f32 v[30:31], v[30:31], v[46:47] op_sel_hi:[1,0]
	v_pk_mul_f32 v[46:47], v[68:69], v[46:47] op_sel_hi:[1,0]
	ds_write2st64_b32 v32, v2, v3 offset0:24 offset1:25
	v_cvt_pk_bf16_f32 v2, v62, v63
	v_cvt_pk_bf16_f32 v3, v14, v15
	ds_write2st64_b32 v32, v2, v3 offset0:26 offset1:27
	v_cvt_pk_bf16_f32 v2, v30, v31
	v_cvt_pk_bf16_f32 v3, v46, v47
	ds_write2st64_b32 v32, v2, v3 offset0:28 offset1:29
	v_cvt_pk_bf16_f32 v2, v64, v65
	v_cvt_pk_bf16_f32 v3, v16, v17
	ds_write2st64_b32 v32, v2, v3 offset0:30 offset1:31
	v_mov_b32_e32 v16, v1
	v_mov_b32_e32 v17, v1
	v_mov_b32_e32 v2, v1
	v_mov_b32_e32 v3, v1
	v_mov_b32_e32 v4, v1
	v_mov_b32_e32 v5, v1
	v_mov_b32_e32 v6, v1
	v_mov_b32_e32 v7, v1
	v_mov_b32_e32 v8, v1
	v_mov_b32_e32 v9, v1
	v_mov_b32_e32 v10, v1
	v_mov_b32_e32 v11, v1
	v_mov_b32_e32 v12, v1
	v_mov_b32_e32 v13, v1
	v_mov_b32_e32 v14, v1
	v_mov_b32_e32 v15, v1
	v_mov_b64_e32 v[64:65], v[16:17]
	v_mov_b64_e32 v[32:33], v[16:17]
	v_mov_b64_e32 v[48:49], v[16:17]
	v_mov_b64_e32 v[80:81], v[16:17]
	v_lshl_add_u64 v[150:151], s[46:47], 0, v[158:159]
	s_mov_b32 s4, 0
	s_mov_b32 s22, 1
	v_mov_b64_e32 v[62:63], v[14:15]
	v_mov_b64_e32 v[60:61], v[12:13]
	v_mov_b64_e32 v[58:59], v[10:11]
	v_mov_b64_e32 v[56:57], v[8:9]
	v_mov_b64_e32 v[54:55], v[6:7]
	v_mov_b64_e32 v[52:53], v[4:5]
	v_mov_b64_e32 v[50:51], v[2:3]
	v_mov_b64_e32 v[30:31], v[14:15]
	v_mov_b64_e32 v[28:29], v[12:13]
	v_mov_b64_e32 v[26:27], v[10:11]
	v_mov_b64_e32 v[24:25], v[8:9]
	v_mov_b64_e32 v[22:23], v[6:7]
	v_mov_b64_e32 v[20:21], v[4:5]
	v_mov_b64_e32 v[18:19], v[2:3]
	v_mov_b64_e32 v[46:47], v[14:15]
	v_mov_b64_e32 v[44:45], v[12:13]
	v_mov_b64_e32 v[42:43], v[10:11]
	v_mov_b64_e32 v[40:41], v[8:9]
	v_mov_b64_e32 v[38:39], v[6:7]
	v_mov_b64_e32 v[36:37], v[4:5]
	v_mov_b64_e32 v[34:35], v[2:3]
	v_mov_b64_e32 v[78:79], v[14:15]
	v_mov_b64_e32 v[76:77], v[12:13]
	v_mov_b64_e32 v[74:75], v[10:11]
	v_mov_b64_e32 v[72:73], v[8:9]
	v_mov_b64_e32 v[70:71], v[6:7]
	v_mov_b64_e32 v[68:69], v[4:5]
	v_mov_b64_e32 v[66:67], v[2:3]
	s_waitcnt vmcnt(6)
	ds_write_b128 v238, v[114:117]
	s_waitcnt vmcnt(5)
	ds_write_b128 v239, v[130:133] offset:9216
	s_waitcnt vmcnt(4)
	ds_write_b128 v240, v[138:141] offset:9216
	s_waitcnt vmcnt(0) lgkmcnt(0)
	s_barrier
	v_mov_b32_e32 v238, 0
	s_mov_b32 s79, 1
	s_cmp_lt_u32 s22, s5
	s_cselect_b64 s[28:29], -1, 0
	s_cmp_ge_u32 s22, s5
	s_cbranch_scc1 .LBB0_81
